# DSA selection final pass: candidate indices read once before the threshold search instead of a read+wait inside each of the 16 steps
# baseline (speedup 1.0000x reference)
.LBB0_2424:
	s_add_i32 s6, s56, 63
	s_lshr_b32 s57, s6, 6
	v_cmp_gt_u32_e64 s[10:11], s56, v186
	v_cmp_gt_u32_e64 s[8:9], s56, v194
	v_cmp_gt_u32_e64 s[6:7], s56, v195
	s_waitcnt lgkmcnt(0)
	v_cndmask_b32_e64 v17, 0, v2, s[10:11]
	v_cndmask_b32_e64 v3, 0, v3, s[8:9]
	v_cndmask_b32_e64 v2, 0, v18, s[6:7]
	v_mov_b32_e32 v18, 31
	ds_read_b32 v20, v190 offset:4096
	ds_read_b32 v21, v190 offset:4352
	ds_read_b32 v22, v190 offset:4608
	ds_read_b32 v23, v190 offset:4864
	ds_read_b32 v24, v190 offset:5120
	ds_read_b32 v25, v190 offset:5376
	ds_read_b32 v26, v190 offset:5632
	ds_read_b32 v27, v190 offset:5888
	ds_read_b32 v28, v190 offset:6144
	ds_read_b32 v29, v190 offset:6400
	ds_read_b32 v30, v190 offset:6656
	ds_read_b32 v31, v190 offset:6912
	ds_read_b32 v32, v190 offset:7168
	ds_read_b32 v33, v190 offset:7424
	ds_read_b32 v34, v190 offset:7680
	ds_read_b32 v35, v190 offset:7936
	s_branch .LBB0_2426

.LBB0_2452:
	s_sub_i32 s58, 0x100, s12
	s_waitcnt lgkmcnt(0)
	s_cmp_lt_i32 s57, 1
	s_cbranch_scc1 .LBB0_2598
	v_cmp_eq_u32_e32 vcc, v17, v0
	s_and_b64 s[10:11], s[10:11], vcc
	v_cndmask_b32_e64 v18, 0, 1, s[10:11]
	v_cmp_ne_u32_e32 vcc, 0, v18
	s_nop 1
	v_mbcnt_lo_u32_b32 v19, vcc_lo, 0
	v_mbcnt_hi_u32_b32 v18, vcc_hi, v19
	v_cmp_gt_u32_e64 s[12:13], s58, v18
	s_nop 1
	v_cndmask_b32_e64 v18, 0, 1, s[12:13]
	v_cmp_gt_u32_e64 s[12:13], v17, v0
	s_nop 1
	v_cndmask_b32_e64 v17, 0, 1, s[12:13]
	v_cndmask_b32_e64 v17, v17, v18, s[10:11]
	v_and_b32_e32 v17, 1, v17
	v_cmp_eq_u32_e64 s[12:13], 1, v17
	v_cmp_ne_u32_e64 s[10:11], 0, v17
	s_and_saveexec_b64 s[40:41], s[12:13]
	s_cbranch_execz .LBB0_2455
	v_mov_b32_e32 v18, v20
	v_mbcnt_lo_u32_b32 v19, s10, 0
	v_mbcnt_hi_u32_b32 v17, s11, v19
	v_lshl_add_u32 v17, v17, 2, s43
	ds_write_b32 v17, v18

.LBB0_2456:
	v_cmp_eq_u32_e32 vcc, v3, v0
	s_and_b64 s[8:9], vcc, s[8:9]
	v_cndmask_b32_e64 v17, 0, 1, s[8:9]
	v_cmp_ne_u32_e32 vcc, 0, v17
	s_nop 1
	v_mbcnt_lo_u32_b32 v18, vcc_lo, 0
	v_mbcnt_hi_u32_b32 v17, vcc_hi, v18
	v_add_u32_e32 v17, s41, v17
	v_cmp_gt_u32_e64 s[10:11], s58, v17
	s_nop 1
	v_cndmask_b32_e64 v17, 0, 1, s[10:11]
	v_cmp_gt_u32_e64 s[10:11], v3, v0
	s_nop 1
	v_cndmask_b32_e64 v3, 0, 1, s[10:11]
	v_cndmask_b32_e64 v3, v3, v17, s[8:9]
	v_and_b32_e32 v3, 1, v3
	v_cmp_eq_u32_e64 s[10:11], 1, v3
	v_cmp_ne_u32_e64 s[8:9], 0, v3
	s_and_saveexec_b64 s[12:13], s[10:11]
	s_cbranch_execz .LBB0_2458
	v_mov_b32_e32 v17, v21
	v_and_b32_e32 v18, s8, v168
	s_lshl_b32 s10, s40, 2
	v_and_b32_e32 v3, s9, v169
	v_bcnt_u32_b32 v18, v18, 0
	s_add_i32 s10, s43, s10
	v_bcnt_u32_b32 v3, v3, v18
	v_lshl_add_u32 v3, v3, 2, s10
	ds_write_b32 v3, v17

.LBB0_2460:
	v_cmp_eq_u32_e32 vcc, v16, v0
	v_cmp_gt_u32_e64 s[6:7], s56, v196
	s_and_b64 s[6:7], vcc, s[6:7]
	s_nop 0
	v_cndmask_b32_e64 v2, 0, 1, s[6:7]
	v_cmp_ne_u32_e32 vcc, 0, v2
	s_nop 1
	v_mbcnt_lo_u32_b32 v3, vcc_lo, 0
	v_mbcnt_hi_u32_b32 v2, vcc_hi, v3
	v_add_u32_e32 v2, s41, v2
	v_cmp_gt_u32_e64 s[8:9], s58, v2
	s_nop 1
	v_cndmask_b32_e64 v2, 0, 1, s[8:9]
	v_cmp_gt_u32_e64 s[8:9], v16, v0
	s_nop 1
	v_cndmask_b32_e64 v3, 0, 1, s[8:9]
	v_cndmask_b32_e64 v2, v3, v2, s[6:7]
	v_and_b32_e32 v2, 1, v2
	v_cmp_eq_u32_e64 s[8:9], 1, v2
	v_cmp_ne_u32_e64 s[6:7], 0, v2
	s_and_saveexec_b64 s[10:11], s[8:9]
	s_cbranch_execz .LBB0_2462
	v_mov_b32_e32 v3, v23
	v_and_b32_e32 v16, s6, v168
	s_lshl_b32 s8, s40, 2
	v_and_b32_e32 v2, s7, v169
	v_bcnt_u32_b32 v16, v16, 0
	s_add_i32 s8, s43, s8
	v_bcnt_u32_b32 v2, v2, v16
	v_lshl_add_u32 v2, v2, 2, s8
	ds_write_b32 v2, v3

.LBB0_2464:
	v_cmp_eq_u32_e32 vcc, v14, v0
	v_cmp_gt_u32_e64 s[6:7], s56, v198
	s_and_b64 s[6:7], vcc, s[6:7]
	s_nop 0
	v_cndmask_b32_e64 v2, 0, 1, s[6:7]
	v_cmp_ne_u32_e32 vcc, 0, v2
	s_nop 1
	v_mbcnt_lo_u32_b32 v3, vcc_lo, 0
	v_mbcnt_hi_u32_b32 v2, vcc_hi, v3
	v_add_u32_e32 v2, s41, v2
	v_cmp_gt_u32_e64 s[8:9], s58, v2
	s_nop 1
	v_cndmask_b32_e64 v2, 0, 1, s[8:9]
	v_cmp_gt_u32_e64 s[8:9], v14, v0
	s_nop 1
	v_cndmask_b32_e64 v3, 0, 1, s[8:9]
	v_cndmask_b32_e64 v2, v3, v2, s[6:7]
	v_and_b32_e32 v2, 1, v2
	v_cmp_ne_u32_e64 s[6:7], 0, v2
	v_cmp_eq_u32_e64 s[8:9], 1, v2
	s_nop 0
	v_mbcnt_lo_u32_b32 v3, s6, 0
	v_mbcnt_hi_u32_b32 v2, s7, v3
	v_add_u32_e32 v2, s40, v2
	v_cmp_gt_u32_e64 s[10:11], s48, v2
	s_and_b64 s[10:11], s[8:9], s[10:11]
	s_and_saveexec_b64 s[8:9], s[10:11]
	s_cbranch_execz .LBB0_2466
	v_mov_b32_e32 v3, v25
	v_lshl_add_u32 v2, v2, 2, s43
	ds_write_b32 v2, v3

.LBB0_2468:
	v_cmp_eq_u32_e32 vcc, v12, v0
	v_cmp_gt_u32_e64 s[6:7], s56, v200
	s_and_b64 s[6:7], vcc, s[6:7]
	s_nop 0
	v_cndmask_b32_e64 v2, 0, 1, s[6:7]
	v_cmp_ne_u32_e32 vcc, 0, v2
	s_nop 1
	v_mbcnt_lo_u32_b32 v3, vcc_lo, 0
	v_mbcnt_hi_u32_b32 v2, vcc_hi, v3
	v_add_u32_e32 v2, s41, v2
	v_cmp_gt_u32_e64 s[8:9], s58, v2
	s_nop 1
	v_cndmask_b32_e64 v2, 0, 1, s[8:9]
	v_cmp_gt_u32_e64 s[8:9], v12, v0
	s_nop 1
	v_cndmask_b32_e64 v3, 0, 1, s[8:9]
	v_cndmask_b32_e64 v2, v3, v2, s[6:7]
	v_and_b32_e32 v2, 1, v2
	v_cmp_ne_u32_e64 s[6:7], 0, v2
	v_cmp_eq_u32_e64 s[8:9], 1, v2
	s_nop 0
	v_mbcnt_lo_u32_b32 v3, s6, 0
	v_mbcnt_hi_u32_b32 v2, s7, v3
	v_add_u32_e32 v2, s40, v2
	v_cmp_gt_u32_e64 s[10:11], s48, v2
	s_and_b64 s[10:11], s[8:9], s[10:11]
	s_and_saveexec_b64 s[8:9], s[10:11]
	s_cbranch_execz .LBB0_2470
	v_mov_b32_e32 v3, v27
	v_lshl_add_u32 v2, v2, 2, s43
	ds_write_b32 v2, v3

.LBB0_2472:
	v_cmp_eq_u32_e32 vcc, v10, v0
	v_cmp_gt_u32_e64 s[6:7], s56, v202
	s_and_b64 s[6:7], vcc, s[6:7]
	s_nop 0
	v_cndmask_b32_e64 v2, 0, 1, s[6:7]
	v_cmp_ne_u32_e32 vcc, 0, v2
	s_nop 1
	v_mbcnt_lo_u32_b32 v3, vcc_lo, 0
	v_mbcnt_hi_u32_b32 v2, vcc_hi, v3
	v_add_u32_e32 v2, s41, v2
	v_cmp_gt_u32_e64 s[8:9], s58, v2
	s_nop 1
	v_cndmask_b32_e64 v2, 0, 1, s[8:9]
	v_cmp_gt_u32_e64 s[8:9], v10, v0
	s_nop 1
	v_cndmask_b32_e64 v3, 0, 1, s[8:9]
	v_cndmask_b32_e64 v2, v3, v2, s[6:7]
	v_and_b32_e32 v2, 1, v2
	v_cmp_ne_u32_e64 s[6:7], 0, v2
	v_cmp_eq_u32_e64 s[8:9], 1, v2
	s_nop 0
	v_mbcnt_lo_u32_b32 v3, s6, 0
	v_mbcnt_hi_u32_b32 v2, s7, v3
	v_add_u32_e32 v2, s40, v2
	v_cmp_gt_u32_e64 s[10:11], s48, v2
	s_and_b64 s[10:11], s[8:9], s[10:11]
	s_and_saveexec_b64 s[8:9], s[10:11]
	s_cbranch_execz .LBB0_2474
	v_mov_b32_e32 v3, v29
	v_lshl_add_u32 v2, v2, 2, s43
	ds_write_b32 v2, v3

.LBB0_2476:
	v_cmp_eq_u32_e32 vcc, v8, v0
	v_cmp_gt_u32_e64 s[6:7], s56, v204
	s_and_b64 s[6:7], vcc, s[6:7]
	s_nop 0
	v_cndmask_b32_e64 v2, 0, 1, s[6:7]
	v_cmp_ne_u32_e32 vcc, 0, v2
	s_nop 1
	v_mbcnt_lo_u32_b32 v3, vcc_lo, 0
	v_mbcnt_hi_u32_b32 v2, vcc_hi, v3
	v_add_u32_e32 v2, s41, v2
	v_cmp_gt_u32_e64 s[8:9], s58, v2
	s_nop 1
	v_cndmask_b32_e64 v2, 0, 1, s[8:9]
	v_cmp_gt_u32_e64 s[8:9], v8, v0
	s_nop 1
	v_cndmask_b32_e64 v3, 0, 1, s[8:9]
	v_cndmask_b32_e64 v2, v3, v2, s[6:7]
	v_and_b32_e32 v2, 1, v2
	v_cmp_ne_u32_e64 s[6:7], 0, v2
	v_cmp_eq_u32_e64 s[8:9], 1, v2
	s_nop 0
	v_mbcnt_lo_u32_b32 v3, s6, 0
	v_mbcnt_hi_u32_b32 v2, s7, v3
	v_add_u32_e32 v2, s40, v2
	v_cmp_gt_u32_e64 s[10:11], s48, v2
	s_and_b64 s[10:11], s[8:9], s[10:11]
	s_and_saveexec_b64 s[8:9], s[10:11]
	s_cbranch_execz .LBB0_2478
	v_mov_b32_e32 v3, v31
	v_lshl_add_u32 v2, v2, 2, s43
	ds_write_b32 v2, v3

.LBB0_2480:
	v_cmp_eq_u32_e32 vcc, v6, v0
	v_cmp_gt_u32_e64 s[6:7], s56, v206
	s_and_b64 s[6:7], vcc, s[6:7]
	s_nop 0
	v_cndmask_b32_e64 v2, 0, 1, s[6:7]
	v_cmp_ne_u32_e32 vcc, 0, v2
	s_nop 1
	v_mbcnt_lo_u32_b32 v3, vcc_lo, 0
	v_mbcnt_hi_u32_b32 v2, vcc_hi, v3
	v_add_u32_e32 v2, s41, v2
	v_cmp_gt_u32_e64 s[8:9], s58, v2
	s_nop 1
	v_cndmask_b32_e64 v2, 0, 1, s[8:9]
	v_cmp_gt_u32_e64 s[8:9], v6, v0
	s_nop 1
	v_cndmask_b32_e64 v3, 0, 1, s[8:9]
	v_cndmask_b32_e64 v2, v3, v2, s[6:7]
	v_and_b32_e32 v2, 1, v2
	v_cmp_ne_u32_e64 s[6:7], 0, v2
	v_cmp_eq_u32_e64 s[8:9], 1, v2
	s_nop 0
	v_mbcnt_lo_u32_b32 v3, s6, 0
	v_mbcnt_hi_u32_b32 v2, s7, v3
	v_add_u32_e32 v2, s40, v2
	v_cmp_gt_u32_e64 s[10:11], s48, v2
	s_and_b64 s[10:11], s[8:9], s[10:11]
	s_and_saveexec_b64 s[8:9], s[10:11]
	s_cbranch_execz .LBB0_2482
	v_mov_b32_e32 v3, v33
	v_lshl_add_u32 v2, v2, 2, s43
	ds_write_b32 v2, v3

.LBB0_2600:
	v_cmp_eq_u32_e32 vcc, v2, v0
	s_and_b64 s[6:7], vcc, s[6:7]
	v_cndmask_b32_e64 v3, 0, 1, s[6:7]
	v_cmp_ne_u32_e32 vcc, 0, v3
	s_nop 1
	v_mbcnt_lo_u32_b32 v17, vcc_lo, 0
	v_mbcnt_hi_u32_b32 v3, vcc_hi, v17
	v_add_u32_e32 v3, s41, v3
	v_cmp_gt_u32_e64 s[8:9], s58, v3
	s_nop 1
	v_cndmask_b32_e64 v3, 0, 1, s[8:9]
	v_cmp_gt_u32_e64 s[8:9], v2, v0
	s_nop 1
	v_cndmask_b32_e64 v2, 0, 1, s[8:9]
	v_cndmask_b32_e64 v2, v2, v3, s[6:7]
	v_and_b32_e32 v2, 1, v2
	v_cmp_eq_u32_e64 s[8:9], 1, v2
	v_cmp_ne_u32_e64 s[6:7], 0, v2
	s_and_saveexec_b64 s[10:11], s[8:9]
	s_cbranch_execz .LBB0_2602
	v_mov_b32_e32 v3, v22
	v_and_b32_e32 v17, s6, v168
	s_lshl_b32 s8, s40, 2
	v_and_b32_e32 v2, s7, v169
	v_bcnt_u32_b32 v17, v17, 0
	s_add_i32 s8, s43, s8
	v_bcnt_u32_b32 v2, v2, v17
	v_lshl_add_u32 v2, v2, 2, s8
	ds_write_b32 v2, v3

.LBB0_2604:
	v_cmp_eq_u32_e32 vcc, v15, v0
	v_cmp_gt_u32_e64 s[6:7], s56, v197
	s_and_b64 s[6:7], vcc, s[6:7]
	s_nop 0
	v_cndmask_b32_e64 v2, 0, 1, s[6:7]
	v_cmp_ne_u32_e32 vcc, 0, v2
	s_nop 1
	v_mbcnt_lo_u32_b32 v3, vcc_lo, 0
	v_mbcnt_hi_u32_b32 v2, vcc_hi, v3
	v_add_u32_e32 v2, s41, v2
	v_cmp_gt_u32_e64 s[8:9], s58, v2
	s_nop 1
	v_cndmask_b32_e64 v2, 0, 1, s[8:9]
	v_cmp_gt_u32_e64 s[8:9], v15, v0
	s_nop 1
	v_cndmask_b32_e64 v3, 0, 1, s[8:9]
	v_cndmask_b32_e64 v2, v3, v2, s[6:7]
	v_and_b32_e32 v2, 1, v2
	v_cmp_ne_u32_e64 s[6:7], 0, v2
	v_cmp_eq_u32_e64 s[8:9], 1, v2
	s_nop 0
	v_mbcnt_lo_u32_b32 v3, s6, 0
	v_mbcnt_hi_u32_b32 v2, s7, v3
	v_add_u32_e32 v2, s40, v2
	v_cmp_gt_u32_e64 s[10:11], s48, v2
	s_and_b64 s[10:11], s[8:9], s[10:11]
	s_and_saveexec_b64 s[8:9], s[10:11]
	s_cbranch_execz .LBB0_2606
	v_mov_b32_e32 v3, v24
	v_lshl_add_u32 v2, v2, 2, s43
	ds_write_b32 v2, v3

.LBB0_2608:
	v_cmp_eq_u32_e32 vcc, v13, v0
	v_cmp_gt_u32_e64 s[6:7], s56, v199
	s_and_b64 s[6:7], vcc, s[6:7]
	s_nop 0
	v_cndmask_b32_e64 v2, 0, 1, s[6:7]
	v_cmp_ne_u32_e32 vcc, 0, v2
	s_nop 1
	v_mbcnt_lo_u32_b32 v3, vcc_lo, 0
	v_mbcnt_hi_u32_b32 v2, vcc_hi, v3
	v_add_u32_e32 v2, s41, v2
	v_cmp_gt_u32_e64 s[8:9], s58, v2
	s_nop 1
	v_cndmask_b32_e64 v2, 0, 1, s[8:9]
	v_cmp_gt_u32_e64 s[8:9], v13, v0
	s_nop 1
	v_cndmask_b32_e64 v3, 0, 1, s[8:9]
	v_cndmask_b32_e64 v2, v3, v2, s[6:7]
	v_and_b32_e32 v2, 1, v2
	v_cmp_ne_u32_e64 s[6:7], 0, v2
	v_cmp_eq_u32_e64 s[8:9], 1, v2
	s_nop 0
	v_mbcnt_lo_u32_b32 v3, s6, 0
	v_mbcnt_hi_u32_b32 v2, s7, v3
	v_add_u32_e32 v2, s40, v2
	v_cmp_gt_u32_e64 s[10:11], s48, v2
	s_and_b64 s[10:11], s[8:9], s[10:11]
	s_and_saveexec_b64 s[8:9], s[10:11]
	s_cbranch_execz .LBB0_2610
	v_mov_b32_e32 v3, v26
	v_lshl_add_u32 v2, v2, 2, s43
	ds_write_b32 v2, v3

.LBB0_2612:
	v_cmp_eq_u32_e32 vcc, v11, v0
	v_cmp_gt_u32_e64 s[6:7], s56, v201
	s_and_b64 s[6:7], vcc, s[6:7]
	s_nop 0
	v_cndmask_b32_e64 v2, 0, 1, s[6:7]
	v_cmp_ne_u32_e32 vcc, 0, v2
	s_nop 1
	v_mbcnt_lo_u32_b32 v3, vcc_lo, 0
	v_mbcnt_hi_u32_b32 v2, vcc_hi, v3
	v_add_u32_e32 v2, s41, v2
	v_cmp_gt_u32_e64 s[8:9], s58, v2
	s_nop 1
	v_cndmask_b32_e64 v2, 0, 1, s[8:9]
	v_cmp_gt_u32_e64 s[8:9], v11, v0
	s_nop 1
	v_cndmask_b32_e64 v3, 0, 1, s[8:9]
	v_cndmask_b32_e64 v2, v3, v2, s[6:7]
	v_and_b32_e32 v2, 1, v2
	v_cmp_ne_u32_e64 s[6:7], 0, v2
	v_cmp_eq_u32_e64 s[8:9], 1, v2
	s_nop 0
	v_mbcnt_lo_u32_b32 v3, s6, 0
	v_mbcnt_hi_u32_b32 v2, s7, v3
	v_add_u32_e32 v2, s40, v2
	v_cmp_gt_u32_e64 s[10:11], s48, v2
	s_and_b64 s[10:11], s[8:9], s[10:11]
	s_and_saveexec_b64 s[8:9], s[10:11]
	s_cbranch_execz .LBB0_2614
	v_mov_b32_e32 v3, v28
	v_lshl_add_u32 v2, v2, 2, s43
	ds_write_b32 v2, v3

.LBB0_2616:
	v_cmp_eq_u32_e32 vcc, v9, v0
	v_cmp_gt_u32_e64 s[6:7], s56, v203
	s_and_b64 s[6:7], vcc, s[6:7]
	s_nop 0
	v_cndmask_b32_e64 v2, 0, 1, s[6:7]
	v_cmp_ne_u32_e32 vcc, 0, v2
	s_nop 1
	v_mbcnt_lo_u32_b32 v3, vcc_lo, 0
	v_mbcnt_hi_u32_b32 v2, vcc_hi, v3
	v_add_u32_e32 v2, s41, v2
	v_cmp_gt_u32_e64 s[8:9], s58, v2
	s_nop 1
	v_cndmask_b32_e64 v2, 0, 1, s[8:9]
	v_cmp_gt_u32_e64 s[8:9], v9, v0
	s_nop 1
	v_cndmask_b32_e64 v3, 0, 1, s[8:9]
	v_cndmask_b32_e64 v2, v3, v2, s[6:7]
	v_and_b32_e32 v2, 1, v2
	v_cmp_ne_u32_e64 s[6:7], 0, v2
	v_cmp_eq_u32_e64 s[8:9], 1, v2
	s_nop 0
	v_mbcnt_lo_u32_b32 v3, s6, 0
	v_mbcnt_hi_u32_b32 v2, s7, v3
	v_add_u32_e32 v2, s40, v2
	v_cmp_gt_u32_e64 s[10:11], s48, v2
	s_and_b64 s[10:11], s[8:9], s[10:11]
	s_and_saveexec_b64 s[8:9], s[10:11]
	s_cbranch_execz .LBB0_2618
	v_mov_b32_e32 v3, v30
	v_lshl_add_u32 v2, v2, 2, s43
	ds_write_b32 v2, v3

.LBB0_2620:
	v_cmp_eq_u32_e32 vcc, v7, v0
	v_cmp_gt_u32_e64 s[6:7], s56, v205
	s_and_b64 s[6:7], vcc, s[6:7]
	s_nop 0
	v_cndmask_b32_e64 v2, 0, 1, s[6:7]
	v_cmp_ne_u32_e32 vcc, 0, v2
	s_nop 1
	v_mbcnt_lo_u32_b32 v3, vcc_lo, 0
	v_mbcnt_hi_u32_b32 v2, vcc_hi, v3
	v_add_u32_e32 v2, s41, v2
	v_cmp_gt_u32_e64 s[8:9], s58, v2
	s_nop 1
	v_cndmask_b32_e64 v2, 0, 1, s[8:9]
	v_cmp_gt_u32_e64 s[8:9], v7, v0
	s_nop 1
	v_cndmask_b32_e64 v3, 0, 1, s[8:9]
	v_cndmask_b32_e64 v2, v3, v2, s[6:7]
	v_and_b32_e32 v2, 1, v2
	v_cmp_ne_u32_e64 s[6:7], 0, v2
	v_cmp_eq_u32_e64 s[8:9], 1, v2
	s_nop 0
	v_mbcnt_lo_u32_b32 v3, s6, 0
	v_mbcnt_hi_u32_b32 v2, s7, v3
	v_add_u32_e32 v2, s40, v2
	v_cmp_gt_u32_e64 s[10:11], s48, v2
	s_and_b64 s[10:11], s[8:9], s[10:11]
	s_and_saveexec_b64 s[8:9], s[10:11]
	s_cbranch_execz .LBB0_2622
	v_mov_b32_e32 v3, v32
	v_lshl_add_u32 v2, v2, 2, s43
	ds_write_b32 v2, v3

.LBB0_2624:
	v_cmp_eq_u32_e32 vcc, v5, v0
	v_cmp_gt_u32_e64 s[6:7], s56, v207
	s_and_b64 s[6:7], vcc, s[6:7]
	s_nop 0
	v_cndmask_b32_e64 v2, 0, 1, s[6:7]
	v_cmp_ne_u32_e32 vcc, 0, v2
	s_nop 1
	v_mbcnt_lo_u32_b32 v3, vcc_lo, 0
	v_mbcnt_hi_u32_b32 v2, vcc_hi, v3
	v_add_u32_e32 v2, s41, v2
	v_cmp_gt_u32_e64 s[8:9], s58, v2
	s_nop 1
	v_cndmask_b32_e64 v2, 0, 1, s[8:9]
	v_cmp_gt_u32_e64 s[8:9], v5, v0
	s_nop 1
	v_cndmask_b32_e64 v3, 0, 1, s[8:9]
	v_cndmask_b32_e64 v2, v3, v2, s[6:7]
	v_and_b32_e32 v2, 1, v2
	v_cmp_ne_u32_e64 s[6:7], 0, v2
	v_cmp_eq_u32_e64 s[8:9], 1, v2
	s_nop 0
	v_mbcnt_lo_u32_b32 v3, s6, 0
	v_mbcnt_hi_u32_b32 v2, s7, v3
	v_add_u32_e32 v2, s40, v2
	v_cmp_gt_u32_e64 s[10:11], s48, v2
	s_and_b64 s[10:11], s[8:9], s[10:11]
	s_and_saveexec_b64 s[8:9], s[10:11]
	s_cbranch_execz .LBB0_2626
	v_mov_b32_e32 v3, v34
	v_lshl_add_u32 v2, v2, 2, s43
	ds_write_b32 v2, v3

.LBB0_2627:
	v_cmp_eq_u32_e32 vcc, v4, v0
	v_cmp_gt_u32_e64 s[6:7], s56, v208
	s_and_b64 vcc, vcc, s[6:7]
	v_cndmask_b32_e64 v2, 0, 1, vcc
	v_cmp_ne_u32_e64 s[6:7], 0, v2
	s_nop 1
	v_mbcnt_lo_u32_b32 v3, s6, 0
	v_mbcnt_hi_u32_b32 v2, s7, v3
	v_add_u32_e32 v2, s41, v2
	v_cmp_gt_u32_e64 s[6:7], s58, v2
	s_nop 1
	v_cndmask_b32_e64 v2, 0, 1, s[6:7]
	v_cmp_gt_u32_e64 s[6:7], v4, v0
	s_nop 1
	v_cndmask_b32_e64 v0, 0, 1, s[6:7]
	v_cndmask_b32_e32 v0, v0, v2, vcc
	v_and_b32_e32 v0, 1, v0
	v_cmp_ne_u32_e64 s[6:7], 0, v0
	v_cmp_eq_u32_e32 vcc, 1, v0
	s_nop 0
	v_mbcnt_lo_u32_b32 v2, s6, 0
	v_mbcnt_hi_u32_b32 v0, s7, v2
	v_add_u32_e32 v0, s40, v0
	v_cmp_gt_u32_e64 s[6:7], s48, v0
	s_and_b64 s[8:9], vcc, s[6:7]
	s_and_saveexec_b64 s[6:7], s[8:9]
	s_cbranch_execz .LBB0_2629
	v_mov_b32_e32 v2, v35
	v_lshl_add_u32 v0, v0, 2, s43
	ds_write_b32 v0, v2
